# branch A group loop: b_s loads hoisted to the group top and the two vmcnt(0) drains replaced by counted waits so the next group's v / W_s / ug loads stay in flight
# speedup vs baseline: 1.0204x; 1.0030x over previous
; __device__ __forceinline__ u32x4 pack8(const f32x4 a, const f32x4 b) { u32x4 w; w.x = cvt_pk_bf16(a[0], a[1]); w.y = cvt_pk_bf16(a[2], a[3]); w.z = cvt_pk_bf16(b[0], b[1]); w.w = cvt_pk_bf16(b[2], b[3]); return w; }
; #define LAS __attribute__((address_space(3)))
; #define BA_LOAD_UG(g_) do { _Pragma("unroll") for (int i = 0; i < 4; ++i) { const int p = tid + 512 * i, t = p >> 4, dc = p & 15; ugp[i] = *(const u32x4*)(UGQ + (t0 + t) * 2048 + (g_) * 128 + dc * 8); } } while (0)
;     ...
; #pragma unroll
;         for (int j = 0; j < 2; ++j) {
;             const int tb = 2 * tbp + j, t = 32 * tb + r32;
;             const float bias = b_s[g * 128 + t];
;             LAS float* ot = (LAS float*)(lds + BA_OT) + t * 132 + 32 * dblk + 4 * hi;
; #pragma unroll
;             for (int g4 = 0; g4 < 4; ++g4) *(LAS f32x4*)(ot + 8 * g4) = (f32x4){acc[j][4 * g4] + bias, acc[j][4 * g4 + 1] + bias, acc[j][4 * g4 + 2] + bias, acc[j][4 * g4 + 3] + bias};
;         }
;         __syncthreads();
; #pragma unroll
;         for (int i = 0; i < 4; ++i) {
;             const int p = tid + 512 * i, t = p >> 4, dc = p & 15;
;             const LAS float* ot = (const LAS float*)(lds + BA_OT) + t * 132 + dc * 8;
;             const f32x4 m0 = *(const LAS f32x4*)ot, m1 = *(const LAS f32x4*)(ot + 4);
;             bf16* up = UGQ + (t0 + t) * 2048 + g * 128 + dc * 8;
;             f32x4 u0, u1; pg8::unpack8(ugp[i], u0, u1);
;             if (!dry) *(u32x4*)up = pg8::pack8(u0 * m0, u1 * m1);
;         }
;         if (g + 1 < 8) BA_LOAD_UG(g + 1);
.Lba_w3_done:
	s_cmp_eq_u32 s22, 0x38000
	v_pk_add_f32 v[0:1], v[0:1], v[188:189] op_sel_hi:[1,0]
	v_pk_add_f32 v[2:3], v[2:3], v[188:189] op_sel_hi:[1,0]
	ds_write_b128 v167, v[0:3] offset:44032
	v_pk_add_f32 v[0:1], v[4:5], v[188:189] op_sel_hi:[1,0]
	v_pk_add_f32 v[2:3], v[6:7], v[188:189] op_sel_hi:[1,0]
	ds_write_b128 v167, v[0:3] offset:44064
	v_pk_add_f32 v[0:1], v[8:9], v[188:189] op_sel_hi:[1,0]
	v_pk_add_f32 v[2:3], v[10:11], v[188:189] op_sel_hi:[1,0]
	ds_write_b128 v167, v[0:3] offset:44096
	v_pk_add_f32 v[0:1], v[12:13], v[188:189] op_sel_hi:[1,0]
	v_pk_add_f32 v[2:3], v[14:15], v[188:189] op_sel_hi:[1,0]
	ds_write_b128 v167, v[0:3] offset:44128
	v_lshlrev_b32_e32 v10, 16, v60
	v_and_b32_e32 v11, 0xffff0000, v60
	v_lshlrev_b32_e32 v12, 16, v61
	v_and_b32_e32 v13, 0xffff0000, v61
	v_lshlrev_b32_e32 v14, 16, v62
	v_and_b32_e32 v15, 0xffff0000, v62
	v_lshl_add_u64 v[144:145], v[144:145], 0, s[0:1]
	s_mov_b64 s[0:1], 0x100
	v_lshl_add_u64 v[154:155], v[154:155], 0, s[0:1]
	v_lshl_add_u64 v[156:157], v[156:157], 0, s[0:1]
	v_lshl_add_u64 v[158:159], v[158:159], 0, s[0:1]
	v_lshl_add_u64 v[160:161], v[160:161], 0, s[0:1]
	v_pk_add_f32 v[0:1], v[16:17], v[190:191] op_sel_hi:[1,0]
	v_pk_add_f32 v[2:3], v[18:19], v[190:191] op_sel_hi:[1,0]
	ds_write_b128 v167, v[0:3] offset:60928
	v_pk_add_f32 v[0:1], v[20:21], v[190:191] op_sel_hi:[1,0]
	v_pk_add_f32 v[2:3], v[22:23], v[190:191] op_sel_hi:[1,0]
	ds_write_b128 v167, v[0:3] offset:60960
	v_pk_add_f32 v[0:1], v[24:25], v[190:191] op_sel_hi:[1,0]
	v_pk_add_f32 v[2:3], v[26:27], v[190:191] op_sel_hi:[1,0]
	ds_write_b128 v167, v[0:3] offset:60992
	v_pk_add_f32 v[0:1], v[28:29], v[190:191] op_sel_hi:[1,0]
	v_pk_add_f32 v[2:3], v[30:31], v[190:191] op_sel_hi:[1,0]
	ds_write_b128 v167, v[0:3] offset:61024
	s_waitcnt lgkmcnt(0)
	s_barrier
	ds_read_b128 v[2:5], v166 offset:44032
	ds_read_b128 v[6:9], v166 offset:44048
	v_lshlrev_b32_e32 v16, 16, v63
	v_and_b32_e32 v17, 0xffff0000, v63
	v_lshl_add_u64 v[0:1], v[152:153], 0, v[64:65]
	s_waitcnt lgkmcnt(1)
	v_pk_mul_f32 v[4:5], v[4:5], v[12:13]
	v_pk_mul_f32 v[2:3], v[2:3], v[10:11]
	s_waitcnt lgkmcnt(0)
	v_pk_mul_f32 v[8:9], v[8:9], v[16:17]
	v_pk_mul_f32 v[6:7], v[6:7], v[14:15]
	v_cvt_pk_bf16_f32 v2, v2, v3
	v_cvt_pk_bf16_f32 v3, v4, v5
	v_cvt_pk_bf16_f32 v4, v6, v7
	v_cvt_pk_bf16_f32 v5, v8, v9
	global_store_dwordx4 v[0:1], v[2:5], off offset:-256
	ds_read_b128 v[4:7], v165 offset:44032
	ds_read_b128 v[8:11], v165 offset:44048
	v_lshlrev_b32_e32 v12, 16, v44
	v_and_b32_e32 v13, 0xffff0000, v44
	v_lshlrev_b32_e32 v14, 16, v45
	v_and_b32_e32 v15, 0xffff0000, v45
	v_lshlrev_b32_e32 v16, 16, v46
	v_and_b32_e32 v17, 0xffff0000, v46
	v_lshlrev_b32_e32 v18, 16, v47
	v_and_b32_e32 v19, 0xffff0000, v47
	s_waitcnt lgkmcnt(1)
	v_pk_mul_f32 v[6:7], v[6:7], v[14:15]
	v_pk_mul_f32 v[4:5], v[4:5], v[12:13]
	s_waitcnt lgkmcnt(0)
	v_pk_mul_f32 v[10:11], v[10:11], v[18:19]
	v_pk_mul_f32 v[8:9], v[8:9], v[16:17]
	v_lshl_add_u64 v[2:3], v[150:151], 0, v[64:65]
	v_cvt_pk_bf16_f32 v4, v4, v5
	v_cvt_pk_bf16_f32 v5, v6, v7
	v_cvt_pk_bf16_f32 v6, v8, v9
	v_cvt_pk_bf16_f32 v7, v10, v11
	global_store_dwordx4 v[2:3], v[4:7], off offset:-256
	ds_read_b128 v[6:9], v164 offset:44032
	ds_read_b128 v[10:13], v164 offset:44048
	v_lshlrev_b32_e32 v14, 16, v36
	v_and_b32_e32 v15, 0xffff0000, v36
	v_lshlrev_b32_e32 v16, 16, v37
	v_and_b32_e32 v17, 0xffff0000, v37
	v_lshlrev_b32_e32 v18, 16, v38
	v_and_b32_e32 v19, 0xffff0000, v38
	v_lshlrev_b32_e32 v20, 16, v39
	v_and_b32_e32 v21, 0xffff0000, v39
	s_waitcnt lgkmcnt(1)
	v_pk_mul_f32 v[8:9], v[8:9], v[16:17]
	v_pk_mul_f32 v[6:7], v[6:7], v[14:15]
	s_waitcnt lgkmcnt(0)
	v_pk_mul_f32 v[12:13], v[12:13], v[20:21]
	v_pk_mul_f32 v[10:11], v[10:11], v[18:19]
	v_lshl_add_u64 v[4:5], v[148:149], 0, v[64:65]
	v_cvt_pk_bf16_f32 v6, v6, v7
	v_cvt_pk_bf16_f32 v7, v8, v9
	v_cvt_pk_bf16_f32 v8, v10, v11
	v_cvt_pk_bf16_f32 v9, v12, v13
	global_store_dwordx4 v[4:5], v[6:9], off offset:-256
	ds_read_b128 v[6:9], v141 offset:44032
	ds_read_b128 v[10:13], v141 offset:44048
	v_lshlrev_b32_e32 v14, 16, v32
	v_and_b32_e32 v15, 0xffff0000, v32
	v_lshlrev_b32_e32 v16, 16, v33
	v_and_b32_e32 v17, 0xffff0000, v33
	v_lshlrev_b32_e32 v18, 16, v34
	v_and_b32_e32 v19, 0xffff0000, v34
	v_lshlrev_b32_e32 v20, 16, v35
	v_and_b32_e32 v21, 0xffff0000, v35
	s_waitcnt lgkmcnt(1)
	v_pk_mul_f32 v[8:9], v[8:9], v[16:17]
	v_pk_mul_f32 v[6:7], v[6:7], v[14:15]
	s_waitcnt lgkmcnt(0)
	v_pk_mul_f32 v[12:13], v[12:13], v[20:21]
	v_pk_mul_f32 v[10:11], v[10:11], v[18:19]
	v_lshl_add_u64 v[22:23], v[146:147], 0, v[64:65]
	v_cvt_pk_bf16_f32 v6, v6, v7
	v_cvt_pk_bf16_f32 v7, v8, v9
	v_cvt_pk_bf16_f32 v8, v10, v11
	v_cvt_pk_bf16_f32 v9, v12, v13
	global_store_dwordx4 v[22:23], v[6:9], off offset:-256
	global_load_dwordx4 v[60:63], v[0:1], off
	global_load_dwordx4 v[44:47], v[2:3], off
	global_load_dwordx4 v[36:39], v[4:5], off
	global_load_dwordx4 v[32:35], v[22:23], off
	v_lshl_add_u64 v[146:147], v[146:147], 0, s[0:1]
	v_lshl_add_u64 v[148:149], v[148:149], 0, s[0:1]
	v_lshl_add_u64 v[150:151], v[150:151], 0, s[0:1]
	v_lshl_add_u64 v[152:153], v[152:153], 0, s[0:1]
	s_cbranch_scc1 .LBB0_574
; __device__ __forceinline__ u32x4 pack8(const f32x4 a, const f32x4 b) { u32x4 w; w.x = cvt_pk_bf16(a[0], a[1]); w.y = cvt_pk_bf16(a[2], a[3]); w.z = cvt_pk_bf16(b[0], b[1]); w.w = cvt_pk_bf16(b[2], b[3]); return w; }
; #define LAS __attribute__((address_space(3)))
;     ...
;     for (int g = 0; g < 8; ++g) {
;         const f32x4 ga = *(const LAS f32x4*)(gbl + g * 128 + (tid & 15) * 8), gb2 = *(const LAS f32x4*)(gbl + g * 128 + (tid & 15) * 8 + 4);
;         const f32x4 ba = *(const LAS f32x4*)(gbl + 1024 + g * 128 + (tid & 15) * 8), bb2 = *(const LAS f32x4*)(gbl + 1024 + g * 128 + (tid & 15) * 8 + 4);
; #pragma unroll
;         for (int i = 0; i < 4; ++i) {
;             const int p = tid + 512 * i, s = p >> 4, dc = p & 15;
;             f32x4 v0, v1; pg8::unpack8(vpc[i], v0, v1);
;             const float mean = stat[s * 2], rstd = stat[s * 2 + 1];
;             v0 = (v0 - mean) * rstd * ga + ba; v1 = (v1 - mean) * rstd * gb2 + bb2;
;             const u32x4 w = pg8::pack8(v0, v1);
;             LAS unsigned short* dst = (LAS unsigned short*)(lds + BA_VNT) + dc * 136 + s;
;             dst[0 * 16 * 136] = (unsigned short)(w.x & 0xffffu); dst[1 * 16 * 136] = (unsigned short)(w.x >> 16); dst[2 * 16 * 136] = (unsigned short)(w.y & 0xffffu); dst[3 * 16 * 136] = (unsigned short)(w.y >> 16);
;             dst[4 * 16 * 136] = (unsigned short)(w.z & 0xffffu); dst[5 * 16 * 136] = (unsigned short)(w.z >> 16); dst[6 * 16 * 136] = (unsigned short)(w.w & 0xffffu); dst[7 * 16 * 136] = (unsigned short)(w.w >> 16);
;         }
;         if (g + 1 < 8) {
; #pragma unroll
;             for (int i = 0; i < 4; ++i) { const int p = tid + 512 * i, s = p >> 4, dc = p & 15; vpc[i] = *(const u32x4*)(Vb + (t0 + s) * 1024 + (g + 1) * 128 + dc * 8); }
;         }
;         __syncthreads();
;         const int d = 32 * dblk + r32;
;     ...
;             const float bias = b_s[g * 128 + t];
.LBB0_510:
	global_load_dword v188, v[144:145], off offset:-128
	global_load_dword v190, v[144:145], off
	s_waitcnt vmcnt(19)
	ds_read_b128 v[8:11], v176
	ds_read_b128 v[0:3], v176 offset:16
	ds_read_b128 v[12:15], v176 offset:4096
	ds_read_b128 v[4:7], v176 offset:4112
	ds_read_b64 v[16:17], v177
	ds_read_b64 v[182:183], v173
	ds_read_b64 v[184:185], v171
	ds_read_b64 v[186:187], v169
	v_lshlrev_b32_e32 v20, 16, v126
	v_and_b32_e32 v21, 0xffff0000, v126
	v_lshlrev_b32_e32 v18, 16, v127
	v_and_b32_e32 v19, 0xffff0000, v127
	v_lshlrev_b32_e32 v24, 16, v128
	v_and_b32_e32 v25, 0xffff0000, v128
	v_lshlrev_b32_e32 v22, 16, v129
	v_and_b32_e32 v23, 0xffff0000, v129
	s_waitcnt lgkmcnt(0)
	v_sub_f32_e32 v21, v21, v16
	v_sub_f32_e32 v20, v20, v16
	v_sub_f32_e32 v19, v19, v16
	v_sub_f32_e32 v18, v18, v16
	v_pk_mul_f32 v[20:21], v[16:17], v[20:21] op_sel:[1,0]
	v_sub_f32_e32 v23, v23, v16
	v_sub_f32_e32 v22, v22, v16
	v_sub_f32_e32 v25, v25, v16
	v_sub_f32_e32 v24, v24, v16
	v_pk_mul_f32 v[18:19], v[16:17], v[18:19] op_sel:[1,0]
	v_pk_fma_f32 v[20:21], v[8:9], v[20:21], v[12:13]
	v_pk_mul_f32 v[24:25], v[16:17], v[24:25] op_sel:[1,0]
	v_pk_mul_f32 v[16:17], v[16:17], v[22:23] op_sel:[1,0]
	v_pk_fma_f32 v[18:19], v[10:11], v[18:19], v[14:15]
	v_pk_fma_f32 v[16:17], v[2:3], v[16:17], v[6:7]
	v_pk_fma_f32 v[22:23], v[0:1], v[24:25], v[4:5]
	v_cvt_pk_bf16_f32 v20, v20, v21
	v_cvt_pk_bf16_f32 v18, v18, v19
	v_cvt_pk_bf16_f32 v19, v22, v23
	v_cvt_pk_bf16_f32 v16, v16, v17
	ds_write_b16 v174, v20 offset:9216
	ds_write_b16_d16_hi v174, v20 offset:13568
	ds_write_b16 v174, v18 offset:17920
	ds_write_b16_d16_hi v174, v18 offset:22272
	ds_write_b16 v174, v19 offset:26624
	ds_write_b16_d16_hi v174, v19 offset:30976
	ds_write_b16 v174, v16 offset:35328
	ds_write_b16_d16_hi v174, v16 offset:39680
	s_waitcnt vmcnt(18)
	v_lshlrev_b32_e32 v20, 16, v122
	v_and_b32_e32 v21, 0xffff0000, v122
	v_lshlrev_b32_e32 v18, 16, v123
	v_and_b32_e32 v19, 0xffff0000, v123
	v_lshlrev_b32_e32 v24, 16, v124
	v_and_b32_e32 v25, 0xffff0000, v124
	v_lshlrev_b32_e32 v22, 16, v125
	v_and_b32_e32 v23, 0xffff0000, v125
	v_mov_b32_e32 v16, v182
	v_mov_b32_e32 v17, v183
	v_sub_f32_e32 v21, v21, v16
	v_sub_f32_e32 v20, v20, v16
	v_sub_f32_e32 v19, v19, v16
	v_sub_f32_e32 v18, v18, v16
	v_pk_mul_f32 v[20:21], v[16:17], v[20:21] op_sel:[1,0]
	v_sub_f32_e32 v23, v23, v16
	v_sub_f32_e32 v22, v22, v16
	v_sub_f32_e32 v25, v25, v16
	v_sub_f32_e32 v24, v24, v16
	v_pk_mul_f32 v[18:19], v[16:17], v[18:19] op_sel:[1,0]
	v_pk_fma_f32 v[20:21], v[8:9], v[20:21], v[12:13]
	v_pk_mul_f32 v[24:25], v[16:17], v[24:25] op_sel:[1,0]
	v_pk_mul_f32 v[16:17], v[16:17], v[22:23] op_sel:[1,0]
	v_pk_fma_f32 v[18:19], v[10:11], v[18:19], v[14:15]
	v_pk_fma_f32 v[16:17], v[2:3], v[16:17], v[6:7]
	v_pk_fma_f32 v[22:23], v[0:1], v[24:25], v[4:5]
	v_cvt_pk_bf16_f32 v20, v20, v21
	v_cvt_pk_bf16_f32 v18, v18, v19
	v_cvt_pk_bf16_f32 v19, v22, v23
	v_cvt_pk_bf16_f32 v16, v16, v17
	ds_write_b16 v172, v20 offset:9216
	ds_write_b16_d16_hi v172, v20 offset:13568
	ds_write_b16 v172, v18 offset:17920
	ds_write_b16_d16_hi v172, v18 offset:22272
	ds_write_b16 v172, v19 offset:26624
	ds_write_b16_d16_hi v172, v19 offset:30976
	ds_write_b16 v172, v16 offset:35328
	ds_write_b16_d16_hi v172, v16 offset:39680
	s_waitcnt vmcnt(13)
	v_lshlrev_b32_e32 v20, 16, v118
	v_and_b32_e32 v21, 0xffff0000, v118
	v_lshlrev_b32_e32 v18, 16, v119
	v_and_b32_e32 v19, 0xffff0000, v119
	v_lshlrev_b32_e32 v24, 16, v120
	v_and_b32_e32 v25, 0xffff0000, v120
	v_lshlrev_b32_e32 v22, 16, v121
	v_and_b32_e32 v23, 0xffff0000, v121
	v_mov_b32_e32 v16, v184
	v_mov_b32_e32 v17, v185
	v_sub_f32_e32 v21, v21, v16
	v_sub_f32_e32 v20, v20, v16
	v_sub_f32_e32 v19, v19, v16
	v_sub_f32_e32 v18, v18, v16
	v_pk_mul_f32 v[20:21], v[16:17], v[20:21] op_sel:[1,0]
	v_sub_f32_e32 v23, v23, v16
	v_sub_f32_e32 v22, v22, v16
	v_sub_f32_e32 v25, v25, v16
	v_sub_f32_e32 v24, v24, v16
	v_pk_mul_f32 v[18:19], v[16:17], v[18:19] op_sel:[1,0]
	v_pk_fma_f32 v[20:21], v[8:9], v[20:21], v[12:13]
	v_pk_mul_f32 v[24:25], v[16:17], v[24:25] op_sel:[1,0]
	v_pk_mul_f32 v[16:17], v[16:17], v[22:23] op_sel:[1,0]
	v_pk_fma_f32 v[18:19], v[10:11], v[18:19], v[14:15]
	v_pk_fma_f32 v[16:17], v[2:3], v[16:17], v[6:7]
	v_pk_fma_f32 v[22:23], v[0:1], v[24:25], v[4:5]
	v_cvt_pk_bf16_f32 v20, v20, v21
	v_cvt_pk_bf16_f32 v18, v18, v19
	v_cvt_pk_bf16_f32 v19, v22, v23
	v_cvt_pk_bf16_f32 v16, v16, v17
	ds_write_b16 v170, v20 offset:9216
	ds_write_b16_d16_hi v170, v20 offset:13568
	ds_write_b16 v170, v18 offset:17920
	ds_write_b16_d16_hi v170, v18 offset:22272
	ds_write_b16 v170, v19 offset:26624
	ds_write_b16_d16_hi v170, v19 offset:30976
	ds_write_b16 v170, v16 offset:35328
	ds_write_b16_d16_hi v170, v16 offset:39680
	s_waitcnt vmcnt(12)
	v_lshlrev_b32_e32 v20, 16, v114
	v_and_b32_e32 v21, 0xffff0000, v114
	v_lshlrev_b32_e32 v18, 16, v115
	v_and_b32_e32 v19, 0xffff0000, v115
	v_mov_b32_e32 v16, v186
	v_mov_b32_e32 v17, v187
	v_sub_f32_e32 v19, v19, v16
	v_sub_f32_e32 v18, v18, v16
	v_sub_f32_e32 v21, v21, v16
	v_sub_f32_e32 v20, v20, v16
	v_lshlrev_b32_e32 v22, 16, v116
	v_and_b32_e32 v23, 0xffff0000, v116
	v_lshlrev_b32_e32 v24, 16, v117
	v_and_b32_e32 v25, 0xffff0000, v117
	v_pk_mul_f32 v[20:21], v[16:17], v[20:21] op_sel:[1,0]
	v_pk_mul_f32 v[18:19], v[16:17], v[18:19] op_sel:[1,0]
	v_pk_fma_f32 v[8:9], v[8:9], v[20:21], v[12:13]
	v_pk_fma_f32 v[10:11], v[10:11], v[18:19], v[14:15]
	v_sub_f32_e32 v13, v25, v16
	v_sub_f32_e32 v12, v24, v16
	v_sub_f32_e32 v15, v23, v16
	v_sub_f32_e32 v14, v22, v16
	v_pk_mul_f32 v[14:15], v[16:17], v[14:15] op_sel:[1,0]
	v_pk_mul_f32 v[12:13], v[16:17], v[12:13] op_sel:[1,0]
	v_pk_fma_f32 v[0:1], v[0:1], v[14:15], v[4:5]
	v_pk_fma_f32 v[2:3], v[2:3], v[12:13], v[6:7]
	v_cvt_pk_bf16_f32 v4, v8, v9
	v_cvt_pk_bf16_f32 v0, v0, v1
	v_cvt_pk_bf16_f32 v1, v2, v3
	v_cvt_pk_bf16_f32 v5, v10, v11
	ds_write_b16 v168, v4 offset:9216
	ds_write_b16_d16_hi v168, v4 offset:13568
	ds_write_b16 v168, v5 offset:17920
	ds_write_b16_d16_hi v168, v5 offset:22272
	ds_write_b16 v168, v0 offset:26624
	ds_write_b16_d16_hi v168, v0 offset:30976
	ds_write_b16 v168, v1 offset:35328
	ds_write_b16_d16_hi v168, v1 offset:39680
	v_lshl_add_u64 v[0:1], v[156:157], 0, v[64:65]
	global_load_dwordx4 v[126:129], v[0:1], off
	v_lshl_add_u64 v[0:1], v[158:159], 0, v[64:65]
	global_load_dwordx4 v[122:125], v[0:1], off
	v_lshl_add_u64 v[0:1], v[160:161], 0, v[64:65]
	global_load_dwordx4 v[118:121], v[0:1], off
	v_lshl_add_u64 v[0:1], v[154:155], 0, v[64:65]
	global_load_dwordx4 v[114:117], v[0:1], off
	s_and_b64 vcc, exec, s[38:39]
	v_mov_b32_e32 v0, 0
	v_mov_b32_e32 v1, 0
	v_mov_b32_e32 v2, 0
	v_mov_b32_e32 v3, 0
	v_mov_b32_e32 v4, 0
	v_mov_b32_e32 v5, 0
	v_mov_b32_e32 v6, 0
	v_mov_b32_e32 v7, 0
	v_mov_b32_e32 v8, 0
	v_mov_b32_e32 v9, 0
	v_mov_b32_e32 v10, 0
	v_mov_b32_e32 v11, 0
	v_mov_b32_e32 v12, 0
	v_mov_b32_e32 v13, 0
	v_mov_b32_e32 v14, 0
	v_mov_b32_e32 v15, 0
	s_waitcnt vmcnt(10)
	s_waitcnt lgkmcnt(0)
	s_barrier
; #define LAS __attribute__((address_space(3)))
;     ...
;         const int d = 32 * dblk + r32;
;         const LAS unsigned char* ab = lds + BA_VNT + ((d & 7) * 16 + (d >> 3)) * 272 + hi * 16;
;         f32x16 acc[2];
; #pragma unroll
;         for (int j = 0; j < 2; ++j) {
;             const int tb = 2 * tbp + j;
; #pragma unroll
;             for (int r = 0; r < 16; ++r) acc[j][r] = 0.f;
; #pragma unroll
;             for (int ks = 0; ks < 8; ++ks) if (ks < 2 * (tb + 1)) {
;                 const bf16x8 af = *(const LAS bf16x8*)(ab + ks * 32);
;                 acc[j] = __builtin_amdgcn_mfma_f32_32x32x16_bf16(af, wf[j][ks], acc[j], 0, 0, 0);
	v_add_u32_e32 v250, v139, v140
	ds_read_b128 v[206:209], v250 offset:9216
	ds_read_b128 v[210:213], v250 offset:9248
	ds_read_b128 v[214:217], v250 offset:9280
	ds_read_b128 v[218:221], v250 offset:9312
	ds_read_b128 v[222:225], v250 offset:9344
	ds_read_b128 v[226:229], v250 offset:9376
	ds_read_b128 v[242:245], v250 offset:9408
	ds_read_b128 v[246:249], v250 offset:9440
	s_waitcnt lgkmcnt(0)
	s_cbranch_vccnz .LBB0_512
	v_mfma_f32_32x32x16_bf16 v[0:15], v[206:209], v[110:113], 0
